# GEMM consumer: one LDS fragment read interleaved after each of the first 12 MFMAs of a K-half group instead of 12-read bursts
# speedup vs baseline: 1.1478x; 1.0162x over previous
; #define RAW_BARRIER() do { asm volatile("s_waitcnt lgkmcnt(0)" ::: "memory"); __builtin_amdgcn_s_barrier(); asm volatile("" ::: "memory"); } while (0)
; template <int EPI>
; __device__ __forceinline__ void gemm_phase(const Params& p, const u16* __restrict__ A, int lda, const u16* __restrict__ BT, int ldb,
;                            int K, int N, u16* __restrict__ outb, int ldo, int resid_in, int boff) {
;     ...
;     LOADX(0);
;     if (KT > 1) LOADY(1);
;     f32x16 acc00, acc01, acc10, acc11;
;     if (EPI == EPI_RES && !part_unit) {
;       const int cc0 = n0 + wn * 64 + (lane & 31);
;       float* xfq = p.out;
; #pragma unroll
;       for (int i = 0; i < 16; i++) {
;         const int row = m0 + wm * 64 + 4 * (lane >> 5) + (i & 3) + 8 * (i >> 2);
;         const float* ra = resid_in ? xrow(p, row) : (xfq + (size_t)row * 1024);
;         const float* rb = resid_in ? xrow(p, row + 32) : (xfq + (size_t)(row + 32) * 1024);
;         acc00[i] = ra[cc0]; acc01[i] = ra[cc0 + 32];
;         acc10[i] = rb[cc0]; acc11[i] = rb[cc0 + 32];
;       }
;     } else {
; #pragma unroll
;       for (int i = 0; i < 16; i++) { acc00[i] = 0.f; acc01[i] = 0.f; acc10[i] = 0.f; acc11[i] = 0.f; }
;     }
;     float4 pq0 = make_float4(0.f, 0.f, 0.f, 0.f), pq1 = pq0, pq2 = pq0, pq3 = pq0;
;     if (EPI == EPI_SCALE || EPI == EPI_FF1) {
;       const float4* pp = (const float4*)(part + (size_t)(m0 + (tid & 255)) * 16);
;       pq0 = pp[0]; pq1 = pp[1]; pq2 = pp[2]; pq3 = pp[3];
;     }
;     __syncthreads();
;     WRITEX(0);
;     if (KT > 2) LOADX(2);
;     RAW_BARRIER();
;     for (int kt = 0; kt < KT; kt += 2) {
;       if (kt + 1 < KT) WRITEY(1);
;       if (kt + 3 < KT) LOADY(kt + 3);
;       COMPUTE(0);
;       RAW_BARRIER();
;       if (kt + 1 >= KT) break;
;       if (kt + 2 < KT) WRITEX(0);
;       if (kt + 4 < KT) LOADX(kt + 4);
;       COMPUTE(1);
;       RAW_BARRIER();
;     }
.Lgc_loopT:
	v_mfma_f32_16x16x32_bf16 v[0:3], v[194:197], v[178:181], v[0:3]
	ds_read_b128 v[130:133], v226
	v_mfma_f32_16x16x32_bf16 v[4:7], v[198:201], v[178:181], v[4:7]
	ds_read_b128 v[146:149], v228
	v_mfma_f32_16x16x32_bf16 v[8:11], v[202:205], v[178:181], v[8:11]
	ds_read_b128 v[150:153], v228 offset:2048
	v_mfma_f32_16x16x32_bf16 v[12:15], v[206:209], v[178:181], v[12:15]
	ds_read_b128 v[154:157], v228 offset:4096
	v_mfma_f32_16x16x32_bf16 v[16:19], v[210:213], v[178:181], v[16:19]
	ds_read_b128 v[158:161], v228 offset:6144
	v_mfma_f32_16x16x32_bf16 v[20:23], v[214:217], v[178:181], v[20:23]
	ds_read_b128 v[162:165], v228 offset:8192
	v_mfma_f32_16x16x32_bf16 v[24:27], v[218:221], v[178:181], v[24:27]
	ds_read_b128 v[166:169], v228 offset:10240
	v_mfma_f32_16x16x32_bf16 v[28:31], v[222:225], v[178:181], v[28:31]
	ds_read_b128 v[170:173], v228 offset:12288
	v_mfma_f32_16x16x32_bf16 v[32:35], v[194:197], v[182:185], v[32:35]
	ds_read_b128 v[174:177], v228 offset:14336
	v_mfma_f32_16x16x32_bf16 v[36:39], v[198:201], v[182:185], v[36:39]
	ds_read_b128 v[134:137], v226 offset:2048
	v_mfma_f32_16x16x32_bf16 v[40:43], v[202:205], v[182:185], v[40:43]
	ds_read_b128 v[138:141], v226 offset:4096
	v_mfma_f32_16x16x32_bf16 v[44:47], v[206:209], v[182:185], v[44:47]
	ds_read_b128 v[142:145], v226 offset:6144
	v_mfma_f32_16x16x32_bf16 v[48:51], v[210:213], v[182:185], v[48:51]
	v_mfma_f32_16x16x32_bf16 v[52:55], v[214:217], v[182:185], v[52:55]
	v_mfma_f32_16x16x32_bf16 v[56:59], v[218:221], v[182:185], v[56:59]
	v_mfma_f32_16x16x32_bf16 v[60:63], v[222:225], v[182:185], v[60:63]
	v_mfma_f32_16x16x32_bf16 v[64:67], v[194:197], v[186:189], v[64:67]
	v_mfma_f32_16x16x32_bf16 v[68:71], v[198:201], v[186:189], v[68:71]
	v_mfma_f32_16x16x32_bf16 v[72:75], v[202:205], v[186:189], v[72:75]
	v_mfma_f32_16x16x32_bf16 v[76:79], v[206:209], v[186:189], v[76:79]
	v_mfma_f32_16x16x32_bf16 v[80:83], v[210:213], v[186:189], v[80:83]
	v_mfma_f32_16x16x32_bf16 v[84:87], v[214:217], v[186:189], v[84:87]
	v_mfma_f32_16x16x32_bf16 v[88:91], v[218:221], v[186:189], v[88:91]
	v_mfma_f32_16x16x32_bf16 v[92:95], v[222:225], v[186:189], v[92:95]
	v_mfma_f32_16x16x32_bf16 v[96:99], v[194:197], v[190:193], v[96:99]
	v_mfma_f32_16x16x32_bf16 v[100:103], v[198:201], v[190:193], v[100:103]
	v_mfma_f32_16x16x32_bf16 v[104:107], v[202:205], v[190:193], v[104:107]
	v_mfma_f32_16x16x32_bf16 v[108:111], v[206:209], v[190:193], v[108:111]
	v_mfma_f32_16x16x32_bf16 v[112:115], v[210:213], v[190:193], v[112:115]
	v_mfma_f32_16x16x32_bf16 v[116:119], v[214:217], v[190:193], v[116:119]
	v_mfma_f32_16x16x32_bf16 v[120:123], v[218:221], v[190:193], v[120:123]
	v_mfma_f32_16x16x32_bf16 v[124:127], v[222:225], v[190:193], v[124:127]
	s_waitcnt lgkmcnt(0)
	v_mfma_f32_16x16x32_bf16 v[0:3], v[146:149], v[130:133], v[0:3]
	ds_read_b128 v[178:181], v227
	v_mfma_f32_16x16x32_bf16 v[4:7], v[150:153], v[130:133], v[4:7]
	ds_read_b128 v[194:197], v229
	v_mfma_f32_16x16x32_bf16 v[8:11], v[154:157], v[130:133], v[8:11]
	ds_read_b128 v[198:201], v229 offset:2048
	v_mfma_f32_16x16x32_bf16 v[12:15], v[158:161], v[130:133], v[12:15]
	ds_read_b128 v[202:205], v229 offset:4096
	v_mfma_f32_16x16x32_bf16 v[16:19], v[162:165], v[130:133], v[16:19]
	ds_read_b128 v[206:209], v229 offset:6144
	v_mfma_f32_16x16x32_bf16 v[20:23], v[166:169], v[130:133], v[20:23]
	ds_read_b128 v[210:213], v229 offset:8192
	v_mfma_f32_16x16x32_bf16 v[24:27], v[170:173], v[130:133], v[24:27]
	ds_read_b128 v[214:217], v229 offset:10240
	v_mfma_f32_16x16x32_bf16 v[28:31], v[174:177], v[130:133], v[28:31]
	ds_read_b128 v[218:221], v229 offset:12288
	v_mfma_f32_16x16x32_bf16 v[32:35], v[146:149], v[134:137], v[32:35]
	ds_read_b128 v[222:225], v229 offset:14336
	v_mfma_f32_16x16x32_bf16 v[36:39], v[150:153], v[134:137], v[36:39]
	ds_read_b128 v[182:185], v227 offset:2048
	v_mfma_f32_16x16x32_bf16 v[40:43], v[154:157], v[134:137], v[40:43]
	ds_read_b128 v[186:189], v227 offset:4096
	v_mfma_f32_16x16x32_bf16 v[44:47], v[158:161], v[134:137], v[44:47]
	ds_read_b128 v[190:193], v227 offset:6144
	v_mfma_f32_16x16x32_bf16 v[48:51], v[162:165], v[134:137], v[48:51]
	v_add_u32_e32 v226, s31, v226
	v_mfma_f32_16x16x32_bf16 v[52:55], v[166:169], v[134:137], v[52:55]
	v_add_u32_e32 v227, s31, v227
	v_mfma_f32_16x16x32_bf16 v[56:59], v[170:173], v[134:137], v[56:59]
	v_add_u32_e32 v228, s31, v228
	v_mfma_f32_16x16x32_bf16 v[60:63], v[174:177], v[134:137], v[60:63]
	v_add_u32_e32 v229, s31, v229
	v_mfma_f32_16x16x32_bf16 v[64:67], v[146:149], v[138:141], v[64:67]
	v_mfma_f32_16x16x32_bf16 v[68:71], v[150:153], v[138:141], v[68:71]
	v_mfma_f32_16x16x32_bf16 v[72:75], v[154:157], v[138:141], v[72:75]
	v_mfma_f32_16x16x32_bf16 v[76:79], v[158:161], v[138:141], v[76:79]
	v_mfma_f32_16x16x32_bf16 v[80:83], v[162:165], v[138:141], v[80:83]
	v_mfma_f32_16x16x32_bf16 v[84:87], v[166:169], v[138:141], v[84:87]
	v_mfma_f32_16x16x32_bf16 v[88:91], v[170:173], v[138:141], v[88:91]
	v_mfma_f32_16x16x32_bf16 v[92:95], v[174:177], v[138:141], v[92:95]
	v_mfma_f32_16x16x32_bf16 v[96:99], v[146:149], v[142:145], v[96:99]
	v_mfma_f32_16x16x32_bf16 v[100:103], v[150:153], v[142:145], v[100:103]
	v_mfma_f32_16x16x32_bf16 v[104:107], v[154:157], v[142:145], v[104:107]
	v_mfma_f32_16x16x32_bf16 v[108:111], v[158:161], v[142:145], v[108:111]
	v_mfma_f32_16x16x32_bf16 v[112:115], v[162:165], v[142:145], v[112:115]
	v_mfma_f32_16x16x32_bf16 v[116:119], v[166:169], v[142:145], v[116:119]
	v_mfma_f32_16x16x32_bf16 v[120:123], v[170:173], v[142:145], v[120:123]
	v_mfma_f32_16x16x32_bf16 v[124:127], v[174:177], v[142:145], v[124:127]
	s_add_u32 s13, s13, 1
	s_cmp_eq_u32 s13, 3
	s_cselect_b32 s13, 0, s13
	s_cmp_eq_u32 s13, 2
	s_cselect_b32 s31, s34, s35
	s_waitcnt lgkmcnt(0)
	s_barrier
; template <int EPI> ...
;     ...
;     if (EPI == EPI_SCALE || EPI == EPI_PLAIN || EPI == EPI_FF1) {
; #pragma unroll
;       for (int i = 0; i < 16; i++) {
;         const int rl = rbase + (i & 3) + 8 * (i >> 2);
;         const int row = m0 + rl;
;         float v0 = acc0[i], v1 = acc1[i];
;         if (EPI != EPI_PLAIN) { float rs = sRs[rl]; v0 *= rs; v1 *= rs; }
;         if (EPI == EPI_FF1) { v0 = fmaxf(v0, 0.f); v1 = fmaxf(v1, 0.f); v0 *= v0; v1 *= v1; }
;         outb[(size_t)row * ldo + c0] = f2bf(v0);
;         outb[(size_t)row * ldo + c1] = f2bf(v1);
;       }
; template <int EPI>
; __device__ __forceinline__ void gemm_phase(const Params& p, const u16* __restrict__ A, int lda, const u16* __restrict__ BT, int ldb,
;                            int K, int N, u16* __restrict__ outb, int ldo, int resid_in, int boff) {
;     ...
;     if (EPI == EPI_SCALE || EPI == EPI_FF1) {
;       if (tid < 256) {
;         const float sq = (pq0.x + pq0.y + pq0.z + pq0.w) + (pq1.x + pq1.y + pq1.z + pq1.w) + (pq2.x + pq2.y + pq2.z + pq2.w) + (pq3.x + pq3.y + pq3.z + pq3.w);
;         sRs[tid] = rsqrtf(sq * (1.0f / 1024.0f) + 1e-6f);
;       }
	s_sub_u32 s18, s18, 1
	s_cmp_lg_u32 s18, 0
	s_cbranch_scc1 .Lgc_loopT
	v_mfma_f32_16x16x32_bf16 v[0:3], v[194:197], v[178:181], v[0:3]
	v_mfma_f32_16x16x32_bf16 v[4:7], v[198:201], v[178:181], v[4:7]
	v_mfma_f32_16x16x32_bf16 v[8:11], v[202:205], v[178:181], v[8:11]
	v_mfma_f32_16x16x32_bf16 v[12:15], v[206:209], v[178:181], v[12:15]
	v_mfma_f32_16x16x32_bf16 v[16:19], v[210:213], v[178:181], v[16:19]
	v_mfma_f32_16x16x32_bf16 v[20:23], v[214:217], v[178:181], v[20:23]
	v_mfma_f32_16x16x32_bf16 v[24:27], v[218:221], v[178:181], v[24:27]
	v_mfma_f32_16x16x32_bf16 v[28:31], v[222:225], v[178:181], v[28:31]
	v_mfma_f32_16x16x32_bf16 v[32:35], v[194:197], v[182:185], v[32:35]
	v_mfma_f32_16x16x32_bf16 v[36:39], v[198:201], v[182:185], v[36:39]
	v_mfma_f32_16x16x32_bf16 v[40:43], v[202:205], v[182:185], v[40:43]
	v_mfma_f32_16x16x32_bf16 v[44:47], v[206:209], v[182:185], v[44:47]
	v_mfma_f32_16x16x32_bf16 v[48:51], v[210:213], v[182:185], v[48:51]
	v_mfma_f32_16x16x32_bf16 v[52:55], v[214:217], v[182:185], v[52:55]
	v_mfma_f32_16x16x32_bf16 v[56:59], v[218:221], v[182:185], v[56:59]
	v_mfma_f32_16x16x32_bf16 v[60:63], v[222:225], v[182:185], v[60:63]
	v_mfma_f32_16x16x32_bf16 v[64:67], v[194:197], v[186:189], v[64:67]
	v_mfma_f32_16x16x32_bf16 v[68:71], v[198:201], v[186:189], v[68:71]
	v_mfma_f32_16x16x32_bf16 v[72:75], v[202:205], v[186:189], v[72:75]
	v_mfma_f32_16x16x32_bf16 v[76:79], v[206:209], v[186:189], v[76:79]
	v_mfma_f32_16x16x32_bf16 v[80:83], v[210:213], v[186:189], v[80:83]
	v_mfma_f32_16x16x32_bf16 v[84:87], v[214:217], v[186:189], v[84:87]
	v_mfma_f32_16x16x32_bf16 v[88:91], v[218:221], v[186:189], v[88:91]
	v_mfma_f32_16x16x32_bf16 v[92:95], v[222:225], v[186:189], v[92:95]
	v_mfma_f32_16x16x32_bf16 v[96:99], v[194:197], v[190:193], v[96:99]
	v_mfma_f32_16x16x32_bf16 v[100:103], v[198:201], v[190:193], v[100:103]
	v_mfma_f32_16x16x32_bf16 v[104:107], v[202:205], v[190:193], v[104:107]
	v_mfma_f32_16x16x32_bf16 v[108:111], v[206:209], v[190:193], v[108:111]
	v_mfma_f32_16x16x32_bf16 v[112:115], v[210:213], v[190:193], v[112:115]
	v_mfma_f32_16x16x32_bf16 v[116:119], v[214:217], v[190:193], v[116:119]
	v_mfma_f32_16x16x32_bf16 v[120:123], v[218:221], v[190:193], v[120:123]
	v_mfma_f32_16x16x32_bf16 v[124:127], v[222:225], v[190:193], v[124:127]
	s_cmp_eq_u32 s30, 3
	s_cbranch_scc1 .Lgc_epi_res
	s_lshl_b32 s11, s6, 8
	s_lshl_b32 s12, s4, 6
	s_add_u32 s11, s11, s12
	v_add_u32_e32 v238, s11, v248
	v_mul_lo_u32 v230, v238, s24
	s_lshl_b32 s11, s7, 7
	v_and_b32_e32 v239, 1, v249
	v_lshrrev_b32_e32 v240, 1, v249
	v_lshlrev_b32_e32 v239, 4, v239
	v_lshl_add_u32 v239, v240, 3, v239
	v_add_u32_e32 v239, s11, v239
	v_lshlrev_b32_e32 v239, 1, v239
	v_add_u32_e32 v230, v230, v239
	s_lshl_b32 s11, s24, 4
	v_add_u32_e32 v231, s11, v230
	v_add_u32_e32 v232, s11, v231
	v_add_u32_e32 v233, s11, v232
	s_nop 7
	v_add_u32_e32 v239, s33, v242
	ds_read_b32 v234, v239
	ds_read_b32 v235, v239 offset:64
	ds_read_b32 v236, v239 offset:128
	ds_read_b32 v237, v239 offset:192
	s_waitcnt lgkmcnt(0)
	v_mul_f32_e32 v0, v0, v234
	v_mul_f32_e32 v1, v1, v234
	v_mul_f32_e32 v2, v2, v234
	v_mul_f32_e32 v3, v3, v234
	v_mul_f32_e32 v4, v4, v234
	v_mul_f32_e32 v5, v5, v234
	v_mul_f32_e32 v6, v6, v234
	v_mul_f32_e32 v7, v7, v234
	v_mul_f32_e32 v8, v8, v234
	v_mul_f32_e32 v9, v9, v234
	v_mul_f32_e32 v10, v10, v234
	v_mul_f32_e32 v11, v11, v234
	v_mul_f32_e32 v12, v12, v234
	v_mul_f32_e32 v13, v13, v234
	v_mul_f32_e32 v14, v14, v234
	v_mul_f32_e32 v15, v15, v234
	v_mul_f32_e32 v16, v16, v234
	v_mul_f32_e32 v17, v17, v234
	v_mul_f32_e32 v18, v18, v234
	v_mul_f32_e32 v19, v19, v234
	v_mul_f32_e32 v20, v20, v234
	v_mul_f32_e32 v21, v21, v234
	v_mul_f32_e32 v22, v22, v234
	v_mul_f32_e32 v23, v23, v234
	v_mul_f32_e32 v24, v24, v234
	v_mul_f32_e32 v25, v25, v234
	v_mul_f32_e32 v26, v26, v234
	v_mul_f32_e32 v27, v27, v234
	v_mul_f32_e32 v28, v28, v234
	v_mul_f32_e32 v29, v29, v234
	v_mul_f32_e32 v30, v30, v234
	v_mul_f32_e32 v31, v31, v234
	v_mul_f32_e32 v32, v32, v235
	v_mul_f32_e32 v33, v33, v235
	v_mul_f32_e32 v34, v34, v235
	v_mul_f32_e32 v35, v35, v235
	v_mul_f32_e32 v36, v36, v235
	v_mul_f32_e32 v37, v37, v235
	v_mul_f32_e32 v38, v38, v235
	v_mul_f32_e32 v39, v39, v235
	v_mul_f32_e32 v40, v40, v235
	v_mul_f32_e32 v41, v41, v235
	v_mul_f32_e32 v42, v42, v235
	v_mul_f32_e32 v43, v43, v235
	v_mul_f32_e32 v44, v44, v235
	v_mul_f32_e32 v45, v45, v235
	v_mul_f32_e32 v46, v46, v235
	v_mul_f32_e32 v47, v47, v235
	v_mul_f32_e32 v48, v48, v235
	v_mul_f32_e32 v49, v49, v235
	v_mul_f32_e32 v50, v50, v235
	v_mul_f32_e32 v51, v51, v235
	v_mul_f32_e32 v52, v52, v235
	v_mul_f32_e32 v53, v53, v235
	v_mul_f32_e32 v54, v54, v235
	v_mul_f32_e32 v55, v55, v235
	v_mul_f32_e32 v56, v56, v235
	v_mul_f32_e32 v57, v57, v235
	v_mul_f32_e32 v58, v58, v235
	v_mul_f32_e32 v59, v59, v235
	v_mul_f32_e32 v60, v60, v235
	v_mul_f32_e32 v61, v61, v235
	v_mul_f32_e32 v62, v62, v235
	v_mul_f32_e32 v63, v63, v235
	v_mul_f32_e32 v64, v64, v236
	v_mul_f32_e32 v65, v65, v236
	v_mul_f32_e32 v66, v66, v236
	v_mul_f32_e32 v67, v67, v236
	v_mul_f32_e32 v68, v68, v236
	v_mul_f32_e32 v69, v69, v236
	v_mul_f32_e32 v70, v70, v236
	v_mul_f32_e32 v71, v71, v236
	v_mul_f32_e32 v72, v72, v236
	v_mul_f32_e32 v73, v73, v236
	v_mul_f32_e32 v74, v74, v236
	v_mul_f32_e32 v75, v75, v236
	v_mul_f32_e32 v76, v76, v236
	v_mul_f32_e32 v77, v77, v236
	v_mul_f32_e32 v78, v78, v236
	v_mul_f32_e32 v79, v79, v236
	v_mul_f32_e32 v80, v80, v236
	v_mul_f32_e32 v81, v81, v236
	v_mul_f32_e32 v82, v82, v236
	v_mul_f32_e32 v83, v83, v236
	v_mul_f32_e32 v84, v84, v236
	v_mul_f32_e32 v85, v85, v236
	v_mul_f32_e32 v86, v86, v236
	v_mul_f32_e32 v87, v87, v236
	v_mul_f32_e32 v88, v88, v236
	v_mul_f32_e32 v89, v89, v236
	v_mul_f32_e32 v90, v90, v236
	v_mul_f32_e32 v91, v91, v236
	v_mul_f32_e32 v92, v92, v236
	v_mul_f32_e32 v93, v93, v236
	v_mul_f32_e32 v94, v94, v236
	v_mul_f32_e32 v95, v95, v236
	v_mul_f32_e32 v96, v96, v237
	v_mul_f32_e32 v97, v97, v237
	v_mul_f32_e32 v98, v98, v237
	v_mul_f32_e32 v99, v99, v237
	v_mul_f32_e32 v100, v100, v237
	v_mul_f32_e32 v101, v101, v237
	v_mul_f32_e32 v102, v102, v237
	v_mul_f32_e32 v103, v103, v237
	v_mul_f32_e32 v104, v104, v237
	v_mul_f32_e32 v105, v105, v237
	v_mul_f32_e32 v106, v106, v237
	v_mul_f32_e32 v107, v107, v237
	v_mul_f32_e32 v108, v108, v237
	v_mul_f32_e32 v109, v109, v237
	v_mul_f32_e32 v110, v110, v237
	v_mul_f32_e32 v111, v111, v237
	v_mul_f32_e32 v112, v112, v237
	v_mul_f32_e32 v113, v113, v237
	v_mul_f32_e32 v114, v114, v237
	v_mul_f32_e32 v115, v115, v237
	v_mul_f32_e32 v116, v116, v237
	v_mul_f32_e32 v117, v117, v237
	v_mul_f32_e32 v118, v118, v237
	v_mul_f32_e32 v119, v119, v237
	v_mul_f32_e32 v120, v120, v237
	v_mul_f32_e32 v121, v121, v237
	v_mul_f32_e32 v122, v122, v237
	v_mul_f32_e32 v123, v123, v237
	v_mul_f32_e32 v124, v124, v237
	v_mul_f32_e32 v125, v125, v237
	v_mul_f32_e32 v126, v126, v237
	v_mul_f32_e32 v127, v127, v237
	s_cmp_eq_u32 s30, 0
	s_cbranch_scc1 .Lgm_norelu
; template <int EPI> ...
;     ...
;     if (EPI == EPI_SCALE || EPI == EPI_PLAIN || EPI == EPI_FF1) {
; #pragma unroll
;       for (int i = 0; i < 16; i++) {
;         const int rl = rbase + (i & 3) + 8 * (i >> 2);
;         const int row = m0 + rl;
;         float v0 = acc0[i], v1 = acc1[i];
;         if (EPI != EPI_PLAIN) { float rs = sRs[rl]; v0 *= rs; v1 *= rs; }
;         if (EPI == EPI_FF1) { v0 = fmaxf(v0, 0.f); v1 = fmaxf(v1, 0.f); v0 *= v0; v1 *= v1; }
;         outb[(size_t)row * ldo + c0] = f2bf(v0);
;         outb[(size_t)row * ldo + c1] = f2bf(v1);
;       }
	v_max_f32_e32 v0, 0, v0
	v_mul_f32_e32 v0, v0, v0
	v_max_f32_e32 v1, 0, v1
	v_mul_f32_e32 v1, v1, v1
	v_max_f32_e32 v2, 0, v2
	v_mul_f32_e32 v2, v2, v2
	v_max_f32_e32 v3, 0, v3
	v_mul_f32_e32 v3, v3, v3
	v_max_f32_e32 v4, 0, v4
	v_mul_f32_e32 v4, v4, v4
	v_max_f32_e32 v5, 0, v5
	v_mul_f32_e32 v5, v5, v5
	v_max_f32_e32 v6, 0, v6
	v_mul_f32_e32 v6, v6, v6
	v_max_f32_e32 v7, 0, v7
	v_mul_f32_e32 v7, v7, v7
	v_max_f32_e32 v8, 0, v8
	v_mul_f32_e32 v8, v8, v8
	v_max_f32_e32 v9, 0, v9
	v_mul_f32_e32 v9, v9, v9
	v_max_f32_e32 v10, 0, v10
	v_mul_f32_e32 v10, v10, v10
	v_max_f32_e32 v11, 0, v11
	v_mul_f32_e32 v11, v11, v11
	v_max_f32_e32 v12, 0, v12
	v_mul_f32_e32 v12, v12, v12
	v_max_f32_e32 v13, 0, v13
	v_mul_f32_e32 v13, v13, v13
	v_max_f32_e32 v14, 0, v14
	v_mul_f32_e32 v14, v14, v14
	v_max_f32_e32 v15, 0, v15
	v_mul_f32_e32 v15, v15, v15
	v_max_f32_e32 v16, 0, v16
	v_mul_f32_e32 v16, v16, v16
	v_max_f32_e32 v17, 0, v17
	v_mul_f32_e32 v17, v17, v17
	v_max_f32_e32 v18, 0, v18
	v_mul_f32_e32 v18, v18, v18
	v_max_f32_e32 v19, 0, v19
	v_mul_f32_e32 v19, v19, v19
	v_max_f32_e32 v20, 0, v20
	v_mul_f32_e32 v20, v20, v20
	v_max_f32_e32 v21, 0, v21
	v_mul_f32_e32 v21, v21, v21
	v_max_f32_e32 v22, 0, v22
	v_mul_f32_e32 v22, v22, v22
	v_max_f32_e32 v23, 0, v23
	v_mul_f32_e32 v23, v23, v23
	v_max_f32_e32 v24, 0, v24
	v_mul_f32_e32 v24, v24, v24
	v_max_f32_e32 v25, 0, v25
	v_mul_f32_e32 v25, v25, v25
	v_max_f32_e32 v26, 0, v26
	v_mul_f32_e32 v26, v26, v26
	v_max_f32_e32 v27, 0, v27
	v_mul_f32_e32 v27, v27, v27
	v_max_f32_e32 v28, 0, v28
	v_mul_f32_e32 v28, v28, v28
	v_max_f32_e32 v29, 0, v29
	v_mul_f32_e32 v29, v29, v29
	v_max_f32_e32 v30, 0, v30
	v_mul_f32_e32 v30, v30, v30
	v_max_f32_e32 v31, 0, v31
	v_mul_f32_e32 v31, v31, v31
	v_max_f32_e32 v32, 0, v32
	v_mul_f32_e32 v32, v32, v32
	v_max_f32_e32 v33, 0, v33
	v_mul_f32_e32 v33, v33, v33
	v_max_f32_e32 v34, 0, v34
	v_mul_f32_e32 v34, v34, v34
	v_max_f32_e32 v35, 0, v35
	v_mul_f32_e32 v35, v35, v35
	v_max_f32_e32 v36, 0, v36
	v_mul_f32_e32 v36, v36, v36
	v_max_f32_e32 v37, 0, v37
	v_mul_f32_e32 v37, v37, v37
	v_max_f32_e32 v38, 0, v38
	v_mul_f32_e32 v38, v38, v38
	v_max_f32_e32 v39, 0, v39
	v_mul_f32_e32 v39, v39, v39
	v_max_f32_e32 v40, 0, v40
	v_mul_f32_e32 v40, v40, v40
	v_max_f32_e32 v41, 0, v41
	v_mul_f32_e32 v41, v41, v41
	v_max_f32_e32 v42, 0, v42
	v_mul_f32_e32 v42, v42, v42
	v_max_f32_e32 v43, 0, v43
	v_mul_f32_e32 v43, v43, v43
	v_max_f32_e32 v44, 0, v44
	v_mul_f32_e32 v44, v44, v44
	v_max_f32_e32 v45, 0, v45
	v_mul_f32_e32 v45, v45, v45
	v_max_f32_e32 v46, 0, v46
	v_mul_f32_e32 v46, v46, v46
	v_max_f32_e32 v47, 0, v47
	v_mul_f32_e32 v47, v47, v47
	v_max_f32_e32 v48, 0, v48
	v_mul_f32_e32 v48, v48, v48
	v_max_f32_e32 v49, 0, v49
	v_mul_f32_e32 v49, v49, v49
	v_max_f32_e32 v50, 0, v50
	v_mul_f32_e32 v50, v50, v50
	v_max_f32_e32 v51, 0, v51
	v_mul_f32_e32 v51, v51, v51
	v_max_f32_e32 v52, 0, v52
	v_mul_f32_e32 v52, v52, v52
	v_max_f32_e32 v53, 0, v53
	v_mul_f32_e32 v53, v53, v53
	v_max_f32_e32 v54, 0, v54
	v_mul_f32_e32 v54, v54, v54
	v_max_f32_e32 v55, 0, v55
	v_mul_f32_e32 v55, v55, v55
	v_max_f32_e32 v56, 0, v56
	v_mul_f32_e32 v56, v56, v56
	v_max_f32_e32 v57, 0, v57
	v_mul_f32_e32 v57, v57, v57
	v_max_f32_e32 v58, 0, v58
	v_mul_f32_e32 v58, v58, v58
	v_max_f32_e32 v59, 0, v59
	v_mul_f32_e32 v59, v59, v59
	v_max_f32_e32 v60, 0, v60
	v_mul_f32_e32 v60, v60, v60
	v_max_f32_e32 v61, 0, v61
	v_mul_f32_e32 v61, v61, v61
	v_max_f32_e32 v62, 0, v62
	v_mul_f32_e32 v62, v62, v62
	v_max_f32_e32 v63, 0, v63
	v_mul_f32_e32 v63, v63, v63
	v_max_f32_e32 v64, 0, v64
	v_mul_f32_e32 v64, v64, v64
	v_max_f32_e32 v65, 0, v65
; template <int EPI> ...
;     ...
;     if (EPI == EPI_SCALE || EPI == EPI_PLAIN || EPI == EPI_FF1) {
; #pragma unroll
;       for (int i = 0; i < 16; i++) {
;         const int rl = rbase + (i & 3) + 8 * (i >> 2);
;         const int row = m0 + rl;
;         float v0 = acc0[i], v1 = acc1[i];
;         if (EPI != EPI_PLAIN) { float rs = sRs[rl]; v0 *= rs; v1 *= rs; }
;         if (EPI == EPI_FF1) { v0 = fmaxf(v0, 0.f); v1 = fmaxf(v1, 0.f); v0 *= v0; v1 *= v1; }
;         outb[(size_t)row * ldo + c0] = f2bf(v0);
;         outb[(size_t)row * ldo + c1] = f2bf(v1);
;       }
	v_mul_f32_e32 v65, v65, v65
	v_max_f32_e32 v66, 0, v66
	v_mul_f32_e32 v66, v66, v66
	v_max_f32_e32 v67, 0, v67
	v_mul_f32_e32 v67, v67, v67
	v_max_f32_e32 v68, 0, v68
	v_mul_f32_e32 v68, v68, v68
	v_max_f32_e32 v69, 0, v69
	v_mul_f32_e32 v69, v69, v69
	v_max_f32_e32 v70, 0, v70
	v_mul_f32_e32 v70, v70, v70
	v_max_f32_e32 v71, 0, v71
	v_mul_f32_e32 v71, v71, v71
	v_max_f32_e32 v72, 0, v72
	v_mul_f32_e32 v72, v72, v72
	v_max_f32_e32 v73, 0, v73
	v_mul_f32_e32 v73, v73, v73
	v_max_f32_e32 v74, 0, v74
	v_mul_f32_e32 v74, v74, v74
	v_max_f32_e32 v75, 0, v75
	v_mul_f32_e32 v75, v75, v75
	v_max_f32_e32 v76, 0, v76
	v_mul_f32_e32 v76, v76, v76
	v_max_f32_e32 v77, 0, v77
	v_mul_f32_e32 v77, v77, v77
	v_max_f32_e32 v78, 0, v78
	v_mul_f32_e32 v78, v78, v78
	v_max_f32_e32 v79, 0, v79
	v_mul_f32_e32 v79, v79, v79
	v_max_f32_e32 v80, 0, v80
	v_mul_f32_e32 v80, v80, v80
	v_max_f32_e32 v81, 0, v81
	v_mul_f32_e32 v81, v81, v81
	v_max_f32_e32 v82, 0, v82
	v_mul_f32_e32 v82, v82, v82
	v_max_f32_e32 v83, 0, v83
	v_mul_f32_e32 v83, v83, v83
	v_max_f32_e32 v84, 0, v84
	v_mul_f32_e32 v84, v84, v84
	v_max_f32_e32 v85, 0, v85
	v_mul_f32_e32 v85, v85, v85
	v_max_f32_e32 v86, 0, v86
	v_mul_f32_e32 v86, v86, v86
	v_max_f32_e32 v87, 0, v87
	v_mul_f32_e32 v87, v87, v87
	v_max_f32_e32 v88, 0, v88
	v_mul_f32_e32 v88, v88, v88
	v_max_f32_e32 v89, 0, v89
	v_mul_f32_e32 v89, v89, v89
	v_max_f32_e32 v90, 0, v90
	v_mul_f32_e32 v90, v90, v90
	v_max_f32_e32 v91, 0, v91
	v_mul_f32_e32 v91, v91, v91
	v_max_f32_e32 v92, 0, v92
	v_mul_f32_e32 v92, v92, v92
	v_max_f32_e32 v93, 0, v93
	v_mul_f32_e32 v93, v93, v93
	v_max_f32_e32 v94, 0, v94
	v_mul_f32_e32 v94, v94, v94
	v_max_f32_e32 v95, 0, v95
	v_mul_f32_e32 v95, v95, v95
	v_max_f32_e32 v96, 0, v96
	v_mul_f32_e32 v96, v96, v96
	v_max_f32_e32 v97, 0, v97
	v_mul_f32_e32 v97, v97, v97
	v_max_f32_e32 v98, 0, v98
	v_mul_f32_e32 v98, v98, v98
	v_max_f32_e32 v99, 0, v99
	v_mul_f32_e32 v99, v99, v99
	v_max_f32_e32 v100, 0, v100
	v_mul_f32_e32 v100, v100, v100
	v_max_f32_e32 v101, 0, v101
	v_mul_f32_e32 v101, v101, v101
	v_max_f32_e32 v102, 0, v102
	v_mul_f32_e32 v102, v102, v102
	v_max_f32_e32 v103, 0, v103
	v_mul_f32_e32 v103, v103, v103
	v_max_f32_e32 v104, 0, v104
	v_mul_f32_e32 v104, v104, v104
	v_max_f32_e32 v105, 0, v105
	v_mul_f32_e32 v105, v105, v105
	v_max_f32_e32 v106, 0, v106
	v_mul_f32_e32 v106, v106, v106
	v_max_f32_e32 v107, 0, v107
	v_mul_f32_e32 v107, v107, v107
	v_max_f32_e32 v108, 0, v108
	v_mul_f32_e32 v108, v108, v108
	v_max_f32_e32 v109, 0, v109
	v_mul_f32_e32 v109, v109, v109
	v_max_f32_e32 v110, 0, v110
	v_mul_f32_e32 v110, v110, v110
	v_max_f32_e32 v111, 0, v111
	v_mul_f32_e32 v111, v111, v111
	v_max_f32_e32 v112, 0, v112
	v_mul_f32_e32 v112, v112, v112
	v_max_f32_e32 v113, 0, v113
	v_mul_f32_e32 v113, v113, v113
	v_max_f32_e32 v114, 0, v114
	v_mul_f32_e32 v114, v114, v114
	v_max_f32_e32 v115, 0, v115
	v_mul_f32_e32 v115, v115, v115
	v_max_f32_e32 v116, 0, v116
	v_mul_f32_e32 v116, v116, v116
	v_max_f32_e32 v117, 0, v117
	v_mul_f32_e32 v117, v117, v117
	v_max_f32_e32 v118, 0, v118
	v_mul_f32_e32 v118, v118, v118
	v_max_f32_e32 v119, 0, v119
	v_mul_f32_e32 v119, v119, v119
	v_max_f32_e32 v120, 0, v120
	v_mul_f32_e32 v120, v120, v120
	v_max_f32_e32 v121, 0, v121
	v_mul_f32_e32 v121, v121, v121
	v_max_f32_e32 v122, 0, v122
	v_mul_f32_e32 v122, v122, v122
	v_max_f32_e32 v123, 0, v123
	v_mul_f32_e32 v123, v123, v123
	v_max_f32_e32 v124, 0, v124
	v_mul_f32_e32 v124, v124, v124
	v_max_f32_e32 v125, 0, v125
	v_mul_f32_e32 v125, v125, v125
	v_max_f32_e32 v126, 0, v126
	v_mul_f32_e32 v126, v126, v126
	v_max_f32_e32 v127, 0, v127
	v_mul_f32_e32 v127, v127, v127

; #define RAW_BARRIER() do { asm volatile("s_waitcnt lgkmcnt(0)" ::: "memory"); __builtin_amdgcn_s_barrier(); asm volatile("" ::: "memory"); } while (0)
; template <int EPI>
; __device__ __forceinline__ void gemm_phase(const Params& p, const u16* __restrict__ A, int lda, const u16* __restrict__ BT, int ldb,
;                            int K, int N, u16* __restrict__ outb, int ldo, int resid_in, int boff) {
;     ...
;     LOADX(0);
;     if (KT > 1) LOADY(1);
;     f32x16 acc00, acc01, acc10, acc11;
;     if (EPI == EPI_RES && !part_unit) {
;       const int cc0 = n0 + wn * 64 + (lane & 31);
;       float* xfq = p.out;
; #pragma unroll
;       for (int i = 0; i < 16; i++) {
;         const int row = m0 + wm * 64 + 4 * (lane >> 5) + (i & 3) + 8 * (i >> 2);
;         const float* ra = resid_in ? xrow(p, row) : (xfq + (size_t)row * 1024);
;         const float* rb = resid_in ? xrow(p, row + 32) : (xfq + (size_t)(row + 32) * 1024);
;         acc00[i] = ra[cc0]; acc01[i] = ra[cc0 + 32];
;         acc10[i] = rb[cc0]; acc11[i] = rb[cc0 + 32];
;       }
;     } else {
; #pragma unroll
;       for (int i = 0; i < 16; i++) { acc00[i] = 0.f; acc01[i] = 0.f; acc10[i] = 0.f; acc11[i] = 0.f; }
;     }
;     float4 pq0 = make_float4(0.f, 0.f, 0.f, 0.f), pq1 = pq0, pq2 = pq0, pq3 = pq0;
;     if (EPI == EPI_SCALE || EPI == EPI_FF1) {
;       const float4* pp = (const float4*)(part + (size_t)(m0 + (tid & 255)) * 16);
;       pq0 = pp[0]; pq1 = pp[1]; pq2 = pp[2]; pq3 = pp[3];
;     }
;     __syncthreads();
;     WRITEX(0);
;     if (KT > 2) LOADX(2);
;     RAW_BARRIER();
;     for (int kt = 0; kt < KT; kt += 2) {
;       if (kt + 1 < KT) WRITEY(1);
;       if (kt + 3 < KT) LOADY(kt + 3);
;       COMPUTE(0);
;       RAW_BARRIER();
;       if (kt + 1 >= KT) break;
;       if (kt + 2 < KT) WRITEX(0);
;       if (kt + 4 < KT) LOADX(kt + 4);
;       COMPUTE(1);
;       RAW_BARRIER();
;     }
.Lgc_loopN:
	v_mfma_f32_16x16x32_bf16 v[0:3], v[178:181], v[194:197], v[0:3]
	ds_read_b128 v[130:133], v226
	v_mfma_f32_16x16x32_bf16 v[4:7], v[178:181], v[198:201], v[4:7]
	ds_read_b128 v[146:149], v228
	v_mfma_f32_16x16x32_bf16 v[8:11], v[178:181], v[202:205], v[8:11]
	ds_read_b128 v[150:153], v228 offset:2048
	v_mfma_f32_16x16x32_bf16 v[12:15], v[178:181], v[206:209], v[12:15]
	ds_read_b128 v[154:157], v228 offset:4096
	v_mfma_f32_16x16x32_bf16 v[16:19], v[178:181], v[210:213], v[16:19]
	ds_read_b128 v[158:161], v228 offset:6144
	v_mfma_f32_16x16x32_bf16 v[20:23], v[178:181], v[214:217], v[20:23]
	ds_read_b128 v[162:165], v228 offset:8192
	v_mfma_f32_16x16x32_bf16 v[24:27], v[178:181], v[218:221], v[24:27]
	ds_read_b128 v[166:169], v228 offset:10240
	v_mfma_f32_16x16x32_bf16 v[28:31], v[178:181], v[222:225], v[28:31]
	ds_read_b128 v[170:173], v228 offset:12288
	v_mfma_f32_16x16x32_bf16 v[32:35], v[182:185], v[194:197], v[32:35]
	ds_read_b128 v[174:177], v228 offset:14336
	v_mfma_f32_16x16x32_bf16 v[36:39], v[182:185], v[198:201], v[36:39]
	ds_read_b128 v[134:137], v226 offset:2048
	v_mfma_f32_16x16x32_bf16 v[40:43], v[182:185], v[202:205], v[40:43]
	ds_read_b128 v[138:141], v226 offset:4096
	v_mfma_f32_16x16x32_bf16 v[44:47], v[182:185], v[206:209], v[44:47]
	ds_read_b128 v[142:145], v226 offset:6144
	v_mfma_f32_16x16x32_bf16 v[48:51], v[182:185], v[210:213], v[48:51]
	v_mfma_f32_16x16x32_bf16 v[52:55], v[182:185], v[214:217], v[52:55]
	v_mfma_f32_16x16x32_bf16 v[56:59], v[182:185], v[218:221], v[56:59]
	v_mfma_f32_16x16x32_bf16 v[60:63], v[182:185], v[222:225], v[60:63]
	v_mfma_f32_16x16x32_bf16 v[64:67], v[186:189], v[194:197], v[64:67]
	v_mfma_f32_16x16x32_bf16 v[68:71], v[186:189], v[198:201], v[68:71]
	v_mfma_f32_16x16x32_bf16 v[72:75], v[186:189], v[202:205], v[72:75]
	v_mfma_f32_16x16x32_bf16 v[76:79], v[186:189], v[206:209], v[76:79]
	v_mfma_f32_16x16x32_bf16 v[80:83], v[186:189], v[210:213], v[80:83]
	v_mfma_f32_16x16x32_bf16 v[84:87], v[186:189], v[214:217], v[84:87]
	v_mfma_f32_16x16x32_bf16 v[88:91], v[186:189], v[218:221], v[88:91]
	v_mfma_f32_16x16x32_bf16 v[92:95], v[186:189], v[222:225], v[92:95]
	v_mfma_f32_16x16x32_bf16 v[96:99], v[190:193], v[194:197], v[96:99]
	v_mfma_f32_16x16x32_bf16 v[100:103], v[190:193], v[198:201], v[100:103]
	v_mfma_f32_16x16x32_bf16 v[104:107], v[190:193], v[202:205], v[104:107]
	v_mfma_f32_16x16x32_bf16 v[108:111], v[190:193], v[206:209], v[108:111]
	v_mfma_f32_16x16x32_bf16 v[112:115], v[190:193], v[210:213], v[112:115]
	v_mfma_f32_16x16x32_bf16 v[116:119], v[190:193], v[214:217], v[116:119]
	v_mfma_f32_16x16x32_bf16 v[120:123], v[190:193], v[218:221], v[120:123]
	v_mfma_f32_16x16x32_bf16 v[124:127], v[190:193], v[222:225], v[124:127]
	s_waitcnt lgkmcnt(0)
	v_mfma_f32_16x16x32_bf16 v[0:3], v[130:133], v[146:149], v[0:3]
	ds_read_b128 v[178:181], v227
	v_mfma_f32_16x16x32_bf16 v[4:7], v[130:133], v[150:153], v[4:7]
	ds_read_b128 v[194:197], v229
	v_mfma_f32_16x16x32_bf16 v[8:11], v[130:133], v[154:157], v[8:11]
	ds_read_b128 v[198:201], v229 offset:2048
	v_mfma_f32_16x16x32_bf16 v[12:15], v[130:133], v[158:161], v[12:15]
	ds_read_b128 v[202:205], v229 offset:4096
	v_mfma_f32_16x16x32_bf16 v[16:19], v[130:133], v[162:165], v[16:19]
	ds_read_b128 v[206:209], v229 offset:6144
	v_mfma_f32_16x16x32_bf16 v[20:23], v[130:133], v[166:169], v[20:23]
	ds_read_b128 v[210:213], v229 offset:8192
	v_mfma_f32_16x16x32_bf16 v[24:27], v[130:133], v[170:173], v[24:27]
	ds_read_b128 v[214:217], v229 offset:10240
	v_mfma_f32_16x16x32_bf16 v[28:31], v[130:133], v[174:177], v[28:31]
	ds_read_b128 v[218:221], v229 offset:12288
	v_mfma_f32_16x16x32_bf16 v[32:35], v[134:137], v[146:149], v[32:35]
	ds_read_b128 v[222:225], v229 offset:14336
	v_mfma_f32_16x16x32_bf16 v[36:39], v[134:137], v[150:153], v[36:39]
	ds_read_b128 v[182:185], v227 offset:2048
	v_mfma_f32_16x16x32_bf16 v[40:43], v[134:137], v[154:157], v[40:43]
	ds_read_b128 v[186:189], v227 offset:4096
	v_mfma_f32_16x16x32_bf16 v[44:47], v[134:137], v[158:161], v[44:47]
	ds_read_b128 v[190:193], v227 offset:6144
	v_mfma_f32_16x16x32_bf16 v[48:51], v[134:137], v[162:165], v[48:51]
	v_add_u32_e32 v226, s31, v226
	v_mfma_f32_16x16x32_bf16 v[52:55], v[134:137], v[166:169], v[52:55]
	v_add_u32_e32 v227, s31, v227
	v_mfma_f32_16x16x32_bf16 v[56:59], v[134:137], v[170:173], v[56:59]
	v_add_u32_e32 v228, s31, v228
	v_mfma_f32_16x16x32_bf16 v[60:63], v[134:137], v[174:177], v[60:63]
	v_add_u32_e32 v229, s31, v229
	v_mfma_f32_16x16x32_bf16 v[64:67], v[138:141], v[146:149], v[64:67]
	v_mfma_f32_16x16x32_bf16 v[68:71], v[138:141], v[150:153], v[68:71]
	v_mfma_f32_16x16x32_bf16 v[72:75], v[138:141], v[154:157], v[72:75]
	v_mfma_f32_16x16x32_bf16 v[76:79], v[138:141], v[158:161], v[76:79]
	v_mfma_f32_16x16x32_bf16 v[80:83], v[138:141], v[162:165], v[80:83]
	v_mfma_f32_16x16x32_bf16 v[84:87], v[138:141], v[166:169], v[84:87]
	v_mfma_f32_16x16x32_bf16 v[88:91], v[138:141], v[170:173], v[88:91]
	v_mfma_f32_16x16x32_bf16 v[92:95], v[138:141], v[174:177], v[92:95]
	v_mfma_f32_16x16x32_bf16 v[96:99], v[142:145], v[146:149], v[96:99]
	v_mfma_f32_16x16x32_bf16 v[100:103], v[142:145], v[150:153], v[100:103]
	v_mfma_f32_16x16x32_bf16 v[104:107], v[142:145], v[154:157], v[104:107]
	v_mfma_f32_16x16x32_bf16 v[108:111], v[142:145], v[158:161], v[108:111]
	v_mfma_f32_16x16x32_bf16 v[112:115], v[142:145], v[162:165], v[112:115]
	v_mfma_f32_16x16x32_bf16 v[116:119], v[142:145], v[166:169], v[116:119]
	v_mfma_f32_16x16x32_bf16 v[120:123], v[142:145], v[170:173], v[120:123]
	v_mfma_f32_16x16x32_bf16 v[124:127], v[142:145], v[174:177], v[124:127]
	s_add_u32 s13, s13, 1
	s_cmp_eq_u32 s13, 3
	s_cselect_b32 s13, 0, s13
	s_cmp_eq_u32 s13, 2
	s_cselect_b32 s31, s34, s35
	s_waitcnt lgkmcnt(0)
	s_barrier
; template <int EPI>
; __device__ __forceinline__ void gemm_phase(const Params& p, const u16* __restrict__ A, int lda, const u16* __restrict__ BT, int ldb,
;                            int K, int N, u16* __restrict__ outb, int ldo, int resid_in, int boff) {
;     ...
;     if (EPI == EPI_RES && part_unit) {
;       float* xfp = p.out;
; #pragma unroll
;       for (int i = 0; i < 16; i++) {
;         const int rl = wm * 64 + 4 * (lane >> 5) + (i & 3) + 8 * (i >> 2);
;         float* r0p = xfp + (size_t)(m0 + rl) * 1024;
;         float* r1p = r0p + (size_t)32 * 1024;
;         atomicAdd(r0p + c0, acc00[i]); atomicAdd(r0p + c1, acc01[i]);
;         atomicAdd(r1p + c0, acc10[i]); atomicAdd(r1p + c1, acc11[i]);
;       }
	s_sub_u32 s18, s18, 1
	s_cmp_lg_u32 s18, 0
	s_cbranch_scc1 .Lgc_loopN
	v_mfma_f32_16x16x32_bf16 v[0:3], v[178:181], v[194:197], v[0:3]
	v_mfma_f32_16x16x32_bf16 v[4:7], v[178:181], v[198:201], v[4:7]
	v_mfma_f32_16x16x32_bf16 v[8:11], v[178:181], v[202:205], v[8:11]
	v_mfma_f32_16x16x32_bf16 v[12:15], v[178:181], v[206:209], v[12:15]
	v_mfma_f32_16x16x32_bf16 v[16:19], v[178:181], v[210:213], v[16:19]
	v_mfma_f32_16x16x32_bf16 v[20:23], v[178:181], v[214:217], v[20:23]
	v_mfma_f32_16x16x32_bf16 v[24:27], v[178:181], v[218:221], v[24:27]
	v_mfma_f32_16x16x32_bf16 v[28:31], v[178:181], v[222:225], v[28:31]
	v_mfma_f32_16x16x32_bf16 v[32:35], v[182:185], v[194:197], v[32:35]
	v_mfma_f32_16x16x32_bf16 v[36:39], v[182:185], v[198:201], v[36:39]
	v_mfma_f32_16x16x32_bf16 v[40:43], v[182:185], v[202:205], v[40:43]
	v_mfma_f32_16x16x32_bf16 v[44:47], v[182:185], v[206:209], v[44:47]
	v_mfma_f32_16x16x32_bf16 v[48:51], v[182:185], v[210:213], v[48:51]
	v_mfma_f32_16x16x32_bf16 v[52:55], v[182:185], v[214:217], v[52:55]
	v_mfma_f32_16x16x32_bf16 v[56:59], v[182:185], v[218:221], v[56:59]
	v_mfma_f32_16x16x32_bf16 v[60:63], v[182:185], v[222:225], v[60:63]
	v_mfma_f32_16x16x32_bf16 v[64:67], v[186:189], v[194:197], v[64:67]
	v_mfma_f32_16x16x32_bf16 v[68:71], v[186:189], v[198:201], v[68:71]
	v_mfma_f32_16x16x32_bf16 v[72:75], v[186:189], v[202:205], v[72:75]
	v_mfma_f32_16x16x32_bf16 v[76:79], v[186:189], v[206:209], v[76:79]
	v_mfma_f32_16x16x32_bf16 v[80:83], v[186:189], v[210:213], v[80:83]
	v_mfma_f32_16x16x32_bf16 v[84:87], v[186:189], v[214:217], v[84:87]
	v_mfma_f32_16x16x32_bf16 v[88:91], v[186:189], v[218:221], v[88:91]
	v_mfma_f32_16x16x32_bf16 v[92:95], v[186:189], v[222:225], v[92:95]
	v_mfma_f32_16x16x32_bf16 v[96:99], v[190:193], v[194:197], v[96:99]
	v_mfma_f32_16x16x32_bf16 v[100:103], v[190:193], v[198:201], v[100:103]
	v_mfma_f32_16x16x32_bf16 v[104:107], v[190:193], v[202:205], v[104:107]
	v_mfma_f32_16x16x32_bf16 v[108:111], v[190:193], v[206:209], v[108:111]
	v_mfma_f32_16x16x32_bf16 v[112:115], v[190:193], v[210:213], v[112:115]
	v_mfma_f32_16x16x32_bf16 v[116:119], v[190:193], v[214:217], v[116:119]
	v_mfma_f32_16x16x32_bf16 v[120:123], v[190:193], v[218:221], v[120:123]
	v_mfma_f32_16x16x32_bf16 v[124:127], v[190:193], v[222:225], v[124:127]
	s_lshl_b32 s11, s6, 8
	s_lshl_b32 s12, s4, 6
	s_add_u32 s11, s11, s12
	v_add_u32_e32 v238, s11, v248
	v_sub_u32_e32 v238, v238, v248
	v_lshl_add_u32 v238, v249, 2, v238
	v_lshlrev_b32_e32 v243, 12, v238
	s_lshl_b32 s11, s7, 7
	v_add_u32_e32 v239, s11, v248
	v_lshlrev_b32_e32 v239, 2, v239
	v_add_u32_e32 v243, v243, v239
	s_nop 7
	s_mov_b32 s36, s94
	s_mov_b32 s37, s95
	global_atomic_add_f32 v243, v0, s[36:37]
	global_atomic_add_f32 v243, v4, s[36:37] offset:64
	global_atomic_add_f32 v243, v8, s[36:37] offset:128
	global_atomic_add_f32 v243, v12, s[36:37] offset:192
	global_atomic_add_f32 v243, v16, s[36:37] offset:256
	global_atomic_add_f32 v243, v20, s[36:37] offset:320
	global_atomic_add_f32 v243, v24, s[36:37] offset:384
	global_atomic_add_f32 v243, v28, s[36:37] offset:448
	s_add_u32 s36, s36, 0x1000
	s_addc_u32 s37, s37, 0
	global_atomic_add_f32 v243, v1, s[36:37]
	global_atomic_add_f32 v243, v5, s[36:37] offset:64
	global_atomic_add_f32 v243, v9, s[36:37] offset:128
	global_atomic_add_f32 v243, v13, s[36:37] offset:192
	global_atomic_add_f32 v243, v17, s[36:37] offset:256
	global_atomic_add_f32 v243, v21, s[36:37] offset:320
	global_atomic_add_f32 v243, v25, s[36:37] offset:384
	global_atomic_add_f32 v243, v29, s[36:37] offset:448
	s_add_u32 s36, s36, 0x1000
	s_addc_u32 s37, s37, 0
	global_atomic_add_f32 v243, v2, s[36:37]
	global_atomic_add_f32 v243, v6, s[36:37] offset:64
	global_atomic_add_f32 v243, v10, s[36:37] offset:128
	global_atomic_add_f32 v243, v14, s[36:37] offset:192
	global_atomic_add_f32 v243, v18, s[36:37] offset:256
	global_atomic_add_f32 v243, v22, s[36:37] offset:320
	global_atomic_add_f32 v243, v26, s[36:37] offset:384
	global_atomic_add_f32 v243, v30, s[36:37] offset:448
	s_add_u32 s36, s36, 0x1000
	s_addc_u32 s37, s37, 0
	global_atomic_add_f32 v243, v3, s[36:37]
	global_atomic_add_f32 v243, v7, s[36:37] offset:64
	global_atomic_add_f32 v243, v11, s[36:37] offset:128
	global_atomic_add_f32 v243, v15, s[36:37] offset:192
	global_atomic_add_f32 v243, v19, s[36:37] offset:256
	global_atomic_add_f32 v243, v23, s[36:37] offset:320
	global_atomic_add_f32 v243, v27, s[36:37] offset:384
	global_atomic_add_f32 v243, v31, s[36:37] offset:448
	s_add_u32 s36, s36, 0xd000
	s_addc_u32 s37, s37, 0
	global_atomic_add_f32 v243, v32, s[36:37]
	global_atomic_add_f32 v243, v36, s[36:37] offset:64
	global_atomic_add_f32 v243, v40, s[36:37] offset:128
	global_atomic_add_f32 v243, v44, s[36:37] offset:192
	global_atomic_add_f32 v243, v48, s[36:37] offset:256
	global_atomic_add_f32 v243, v52, s[36:37] offset:320
	global_atomic_add_f32 v243, v56, s[36:37] offset:384
	global_atomic_add_f32 v243, v60, s[36:37] offset:448
	s_add_u32 s36, s36, 0x1000
	s_addc_u32 s37, s37, 0
	global_atomic_add_f32 v243, v33, s[36:37]
	global_atomic_add_f32 v243, v37, s[36:37] offset:64
	global_atomic_add_f32 v243, v41, s[36:37] offset:128
	global_atomic_add_f32 v243, v45, s[36:37] offset:192
	global_atomic_add_f32 v243, v49, s[36:37] offset:256
	global_atomic_add_f32 v243, v53, s[36:37] offset:320
	global_atomic_add_f32 v243, v57, s[36:37] offset:384
	global_atomic_add_f32 v243, v61, s[36:37] offset:448
	s_add_u32 s36, s36, 0x1000
	s_addc_u32 s37, s37, 0
	global_atomic_add_f32 v243, v34, s[36:37]
	global_atomic_add_f32 v243, v38, s[36:37] offset:64
	global_atomic_add_f32 v243, v42, s[36:37] offset:128
; template <int EPI>
; __device__ __forceinline__ void gemm_phase(const Params& p, const u16* __restrict__ A, int lda, const u16* __restrict__ BT, int ldb,
;                            int K, int N, u16* __restrict__ outb, int ldo, int resid_in, int boff) {
;     ...
;     if (EPI == EPI_RES && part_unit) {
;       float* xfp = p.out;
; #pragma unroll
;       for (int i = 0; i < 16; i++) {
;         const int rl = wm * 64 + 4 * (lane >> 5) + (i & 3) + 8 * (i >> 2);
;         float* r0p = xfp + (size_t)(m0 + rl) * 1024;
;         float* r1p = r0p + (size_t)32 * 1024;
;         atomicAdd(r0p + c0, acc00[i]); atomicAdd(r0p + c1, acc01[i]);
;         atomicAdd(r1p + c0, acc10[i]); atomicAdd(r1p + c1, acc11[i]);
;       }
	global_atomic_add_f32 v243, v46, s[36:37] offset:192
	global_atomic_add_f32 v243, v50, s[36:37] offset:256
	global_atomic_add_f32 v243, v54, s[36:37] offset:320
	global_atomic_add_f32 v243, v58, s[36:37] offset:384
	global_atomic_add_f32 v243, v62, s[36:37] offset:448
	s_add_u32 s36, s36, 0x1000
	s_addc_u32 s37, s37, 0
	global_atomic_add_f32 v243, v35, s[36:37]
	global_atomic_add_f32 v243, v39, s[36:37] offset:64
	global_atomic_add_f32 v243, v43, s[36:37] offset:128
	global_atomic_add_f32 v243, v47, s[36:37] offset:192
	global_atomic_add_f32 v243, v51, s[36:37] offset:256
	global_atomic_add_f32 v243, v55, s[36:37] offset:320
	global_atomic_add_f32 v243, v59, s[36:37] offset:384
	global_atomic_add_f32 v243, v63, s[36:37] offset:448
	s_add_u32 s36, s36, 0xd000
	s_addc_u32 s37, s37, 0
	global_atomic_add_f32 v243, v64, s[36:37]
	global_atomic_add_f32 v243, v68, s[36:37] offset:64
	global_atomic_add_f32 v243, v72, s[36:37] offset:128
	global_atomic_add_f32 v243, v76, s[36:37] offset:192
	global_atomic_add_f32 v243, v80, s[36:37] offset:256
	global_atomic_add_f32 v243, v84, s[36:37] offset:320
	global_atomic_add_f32 v243, v88, s[36:37] offset:384
	global_atomic_add_f32 v243, v92, s[36:37] offset:448
	s_add_u32 s36, s36, 0x1000
	s_addc_u32 s37, s37, 0
	global_atomic_add_f32 v243, v65, s[36:37]
	global_atomic_add_f32 v243, v69, s[36:37] offset:64
	global_atomic_add_f32 v243, v73, s[36:37] offset:128
	global_atomic_add_f32 v243, v77, s[36:37] offset:192
	global_atomic_add_f32 v243, v81, s[36:37] offset:256
	global_atomic_add_f32 v243, v85, s[36:37] offset:320
	global_atomic_add_f32 v243, v89, s[36:37] offset:384
	global_atomic_add_f32 v243, v93, s[36:37] offset:448
	s_add_u32 s36, s36, 0x1000
	s_addc_u32 s37, s37, 0
	global_atomic_add_f32 v243, v66, s[36:37]
	global_atomic_add_f32 v243, v70, s[36:37] offset:64
	global_atomic_add_f32 v243, v74, s[36:37] offset:128
	global_atomic_add_f32 v243, v78, s[36:37] offset:192
	global_atomic_add_f32 v243, v82, s[36:37] offset:256
	global_atomic_add_f32 v243, v86, s[36:37] offset:320
	global_atomic_add_f32 v243, v90, s[36:37] offset:384
	global_atomic_add_f32 v243, v94, s[36:37] offset:448
	s_add_u32 s36, s36, 0x1000
	s_addc_u32 s37, s37, 0
	global_atomic_add_f32 v243, v67, s[36:37]
	global_atomic_add_f32 v243, v71, s[36:37] offset:64
	global_atomic_add_f32 v243, v75, s[36:37] offset:128
	global_atomic_add_f32 v243, v79, s[36:37] offset:192
	global_atomic_add_f32 v243, v83, s[36:37] offset:256
	global_atomic_add_f32 v243, v87, s[36:37] offset:320
	global_atomic_add_f32 v243, v91, s[36:37] offset:384
	global_atomic_add_f32 v243, v95, s[36:37] offset:448
	s_add_u32 s36, s36, 0xd000
	s_addc_u32 s37, s37, 0
	global_atomic_add_f32 v243, v96, s[36:37]
	global_atomic_add_f32 v243, v100, s[36:37] offset:64
	global_atomic_add_f32 v243, v104, s[36:37] offset:128
	global_atomic_add_f32 v243, v108, s[36:37] offset:192
	global_atomic_add_f32 v243, v112, s[36:37] offset:256
	global_atomic_add_f32 v243, v116, s[36:37] offset:320
	global_atomic_add_f32 v243, v120, s[36:37] offset:384
	global_atomic_add_f32 v243, v124, s[36:37] offset:448
	s_add_u32 s36, s36, 0x1000
	s_addc_u32 s37, s37, 0
	global_atomic_add_f32 v243, v97, s[36:37]
	global_atomic_add_f32 v243, v101, s[36:37] offset:64
	global_atomic_add_f32 v243, v105, s[36:37] offset:128
	global_atomic_add_f32 v243, v109, s[36:37] offset:192
	global_atomic_add_f32 v243, v113, s[36:37] offset:256
	global_atomic_add_f32 v243, v117, s[36:37] offset:320
	global_atomic_add_f32 v243, v121, s[36:37] offset:384
	global_atomic_add_f32 v243, v125, s[36:37] offset:448
	s_add_u32 s36, s36, 0x1000
	s_addc_u32 s37, s37, 0
	global_atomic_add_f32 v243, v98, s[36:37]
	global_atomic_add_f32 v243, v102, s[36:37] offset:64
	global_atomic_add_f32 v243, v106, s[36:37] offset:128
	global_atomic_add_f32 v243, v110, s[36:37] offset:192
	global_atomic_add_f32 v243, v114, s[36:37] offset:256
	global_atomic_add_f32 v243, v118, s[36:37] offset:320
	global_atomic_add_f32 v243, v122, s[36:37] offset:384
	global_atomic_add_f32 v243, v126, s[36:37] offset:448
	s_add_u32 s36, s36, 0x1000
	s_addc_u32 s37, s37, 0
	global_atomic_add_f32 v243, v99, s[36:37]
	global_atomic_add_f32 v243, v103, s[36:37] offset:64
	global_atomic_add_f32 v243, v107, s[36:37] offset:128
	global_atomic_add_f32 v243, v111, s[36:37] offset:192
	global_atomic_add_f32 v243, v115, s[36:37] offset:256
	global_atomic_add_f32 v243, v119, s[36:37] offset:320
	global_atomic_add_f32 v243, v123, s[36:37] offset:384
	global_atomic_add_f32 v243, v127, s[36:37] offset:448
	s_nop 3
	v_mov_b64_e32 v[0:1], 0
	v_mov_b64_e32 v[2:3], 0
	v_mov_b64_e32 v[4:5], 0
	v_mov_b64_e32 v[6:7], 0
	v_mov_b64_e32 v[8:9], 0
	v_mov_b64_e32 v[10:11], 0
	v_mov_b64_e32 v[12:13], 0
	v_mov_b64_e32 v[14:15], 0
	v_mov_b64_e32 v[16:17], 0
	v_mov_b64_e32 v[18:19], 0
	v_mov_b64_e32 v[20:21], 0
	v_mov_b64_e32 v[22:23], 0
	v_mov_b64_e32 v[24:25], 0
	v_mov_b64_e32 v[26:27], 0
	v_mov_b64_e32 v[28:29], 0
	v_mov_b64_e32 v[30:31], 0
	v_mov_b64_e32 v[32:33], 0
	v_mov_b64_e32 v[34:35], 0
	v_mov_b64_e32 v[36:37], 0
	v_mov_b64_e32 v[38:39], 0
	v_mov_b64_e32 v[40:41], 0
	v_mov_b64_e32 v[42:43], 0
	v_mov_b64_e32 v[44:45], 0
	v_mov_b64_e32 v[46:47], 0
	v_mov_b64_e32 v[48:49], 0
	v_mov_b64_e32 v[50:51], 0
	v_mov_b64_e32 v[52:53], 0
	v_mov_b64_e32 v[54:55], 0
	v_mov_b64_e32 v[56:57], 0
	v_mov_b64_e32 v[58:59], 0
	v_mov_b64_e32 v[60:61], 0
	v_mov_b64_e32 v[62:63], 0
	v_mov_b64_e32 v[64:65], 0
	v_mov_b64_e32 v[66:67], 0
	v_mov_b64_e32 v[68:69], 0
	v_mov_b64_e32 v[70:71], 0
	v_mov_b64_e32 v[72:73], 0
	v_mov_b64_e32 v[74:75], 0
	v_mov_b64_e32 v[76:77], 0
	v_mov_b64_e32 v[78:79], 0
	v_mov_b64_e32 v[80:81], 0
	v_mov_b64_e32 v[82:83], 0
	v_mov_b64_e32 v[84:85], 0
	v_mov_b64_e32 v[86:87], 0
	v_mov_b64_e32 v[88:89], 0
	v_mov_b64_e32 v[90:91], 0
	v_mov_b64_e32 v[92:93], 0
	v_mov_b64_e32 v[94:95], 0
	v_mov_b64_e32 v[96:97], 0
	v_mov_b64_e32 v[98:99], 0
	v_mov_b64_e32 v[100:101], 0
	v_mov_b64_e32 v[102:103], 0
	v_mov_b64_e32 v[104:105], 0
	v_mov_b64_e32 v[106:107], 0
	v_mov_b64_e32 v[108:109], 0
	v_mov_b64_e32 v[110:111], 0
	v_mov_b64_e32 v[112:113], 0
	v_mov_b64_e32 v[114:115], 0
	v_mov_b64_e32 v[116:117], 0
	v_mov_b64_e32 v[118:119], 0
	v_mov_b64_e32 v[120:121], 0
	v_mov_b64_e32 v[122:123], 0
	v_mov_b64_e32 v[124:125], 0
	v_mov_b64_e32 v[126:127], 0
	v_mov_b64_e32 v[178:179], 0
	v_mov_b64_e32 v[180:181], 0
	v_mov_b64_e32 v[182:183], 0
	v_mov_b64_e32 v[184:185], 0
	v_mov_b64_e32 v[186:187], 0
	v_mov_b64_e32 v[188:189], 0
	v_mov_b64_e32 v[190:191], 0
	v_mov_b64_e32 v[192:193], 0
	v_mov_b64_e32 v[194:195], 0
	v_mov_b64_e32 v[196:197], 0
	v_mov_b64_e32 v[198:199], 0
	v_mov_b64_e32 v[200:201], 0
	v_mov_b64_e32 v[202:203], 0
	v_mov_b64_e32 v[204:205], 0
	v_mov_b64_e32 v[206:207], 0
	v_mov_b64_e32 v[208:209], 0
	v_mov_b64_e32 v[210:211], 0
	v_mov_b64_e32 v[212:213], 0
	v_mov_b64_e32 v[214:215], 0
	v_mov_b64_e32 v[216:217], 0
	v_mov_b64_e32 v[218:219], 0
	v_mov_b64_e32 v[220:221], 0
	v_mov_b64_e32 v[222:223], 0
	v_mov_b64_e32 v[224:225], 0
